# flash unmasked softmax: canonicalising max pair dropped, hazard slots of the row-sum tail filled with the alpha/compare ops, +0 row-sum init folded; routing phase 3 interleaved; same values
# speedup vs baseline: 1.0004x; 1.0004x over previous
.LBB0_865:
	v_max_f32_e32 v0, v96, v97
	v_max3_f32 v0, v0, v98, v99
	v_max3_f32 v0, v0, v100, v101
	v_max3_f32 v0, v0, v102, v103
	v_max3_f32 v0, v0, v104, v105
	v_max3_f32 v0, v0, v106, v107
	v_max3_f32 v0, v0, v108, v109
	v_max3_f32 v0, v0, v110, v111
	v_max3_f32 v0, v0, v80, v81
	v_max3_f32 v0, v0, v82, v83
	v_max3_f32 v0, v0, v84, v85
	v_max3_f32 v0, v0, v86, v87
	v_max3_f32 v0, v0, v88, v89
	v_max3_f32 v0, v0, v90, v91
	v_max3_f32 v0, v0, v92, v93
	v_max3_f32 v0, v0, v94, v95
	v_cndmask_b32_e64 v0, v0, v215, s[0:1]
	ds_bpermute_b32 v1, v165, v0
	s_waitcnt lgkmcnt(0)
	v_max3_f32 v34, v201, v0, v1
	v_cndmask_b32_e64 v30, -v34, v215, s[0:1]
	v_pk_add_f32 v[0:1], v[96:97], v[30:31] op_sel_hi:[1,0]
	v_pk_add_f32 v[2:3], v[98:99], v[30:31] op_sel_hi:[1,0]
	v_exp_f32_e32 v0, v0
	v_exp_f32_e32 v1, v1
	v_pk_add_f32 v[4:5], v[100:101], v[30:31] op_sel_hi:[1,0]
	v_exp_f32_e32 v2, v2
	v_exp_f32_e32 v3, v3
	v_exp_f32_e32 v4, v4
	v_exp_f32_e32 v5, v5
	v_pk_add_f32 v[6:7], v[102:103], v[30:31] op_sel_hi:[1,0]
	v_pk_add_f32 v[8:9], v[104:105], v[30:31] op_sel_hi:[1,0]
	v_exp_f32_e32 v6, v6
	v_exp_f32_e32 v7, v7
	v_exp_f32_e32 v8, v8
	v_exp_f32_e32 v9, v9
	v_pk_add_f32 v[10:11], v[2:3], v[0:1]
	v_pk_add_f32 v[12:13], v[108:109], v[30:31] op_sel_hi:[1,0]
	v_pk_add_f32 v[10:11], v[4:5], v[10:11]
	v_exp_f32_e32 v12, v12
	v_pk_add_f32 v[10:11], v[6:7], v[10:11]
	v_exp_f32_e32 v13, v13
	v_pk_add_f32 v[18:19], v[8:9], v[10:11]
	v_pk_add_f32 v[10:11], v[106:107], v[30:31] op_sel_hi:[1,0]
	v_pk_add_f32 v[14:15], v[110:111], v[30:31] op_sel_hi:[1,0]
	v_exp_f32_e32 v10, v10
	v_exp_f32_e32 v11, v11
	v_exp_f32_e32 v14, v14
	v_exp_f32_e32 v15, v15
	v_pk_add_f32 v[16:17], v[80:81], v[30:31] op_sel_hi:[1,0]
	v_pk_add_f32 v[18:19], v[10:11], v[18:19]
	v_exp_f32_e32 v16, v16
	v_exp_f32_e32 v17, v17
	v_pk_add_f32 v[18:19], v[12:13], v[18:19]
	v_pk_add_f32 v[20:21], v[84:85], v[30:31] op_sel_hi:[1,0]
	v_pk_add_f32 v[18:19], v[14:15], v[18:19]
	v_exp_f32_e32 v20, v20
	v_pk_add_f32 v[26:27], v[16:17], v[18:19]
	v_pk_add_f32 v[18:19], v[82:83], v[30:31] op_sel_hi:[1,0]
	v_exp_f32_e32 v21, v21
	v_exp_f32_e32 v18, v18
	v_exp_f32_e32 v19, v19
	v_pk_add_f32 v[22:23], v[86:87], v[30:31] op_sel_hi:[1,0]
	v_pk_add_f32 v[24:25], v[88:89], v[30:31] op_sel_hi:[1,0]
	v_exp_f32_e32 v22, v22
	v_exp_f32_e32 v23, v23
	v_exp_f32_e32 v24, v24
	v_exp_f32_e32 v25, v25
	v_pk_add_f32 v[26:27], v[18:19], v[26:27]
	v_pk_add_f32 v[28:29], v[92:93], v[30:31] op_sel_hi:[1,0]
	v_pk_add_f32 v[26:27], v[20:21], v[26:27]
	v_exp_f32_e32 v28, v28
	v_pk_add_f32 v[26:27], v[22:23], v[26:27]
	v_exp_f32_e32 v29, v29
	v_pk_add_f32 v[36:37], v[24:25], v[26:27]
	v_pk_add_f32 v[26:27], v[90:91], v[30:31] op_sel_hi:[1,0]
	v_pk_add_f32 v[30:31], v[94:95], v[30:31] op_sel_hi:[1,0]
	v_exp_f32_e32 v26, v26
	v_exp_f32_e32 v27, v27
	v_exp_f32_e32 v30, v30
	v_exp_f32_e32 v31, v31
	v_pk_add_f32 v[36:37], v[26:27], v[36:37]
	v_sub_f32_e32 v32, v201, v34
	v_pk_add_f32 v[36:37], v[28:29], v[36:37]
	v_exp_f32_e32 v32, v32
	v_pk_add_f32 v[36:37], v[30:31], v[36:37]
	v_cmp_gt_f32_e32 vcc, 1.0, v32
	v_add_f32_e32 v36, v36, v37
	v_fmac_f32_e32 v36, v202, v32
	s_cbranch_vccnz .LBB0_860
	s_branch .LBB0_861

.LBB0_867:
	v_max_f32_e32 v0, v96, v97
	v_max3_f32 v0, v0, v98, v99
	v_max3_f32 v0, v0, v100, v101
	v_max3_f32 v0, v0, v102, v103
	v_max3_f32 v0, v0, v104, v105
	v_max3_f32 v0, v0, v106, v107
	v_max3_f32 v0, v0, v108, v109
	v_max3_f32 v0, v0, v110, v111
	v_max3_f32 v0, v0, v80, v81
	v_max3_f32 v0, v0, v82, v83
	v_max3_f32 v0, v0, v84, v85
	v_max3_f32 v0, v0, v86, v87
	v_max3_f32 v0, v0, v88, v89
	v_max3_f32 v0, v0, v90, v91
	v_max3_f32 v0, v0, v92, v93
	v_max3_f32 v0, v0, v94, v95
	v_cndmask_b32_e64 v0, v0, v215, s[0:1]
	ds_bpermute_b32 v1, v165, v0
	s_waitcnt lgkmcnt(0)
	v_max3_f32 v201, v34, v0, v1
	v_cndmask_b32_e64 v30, -v201, v215, s[0:1]
	v_pk_add_f32 v[0:1], v[96:97], v[30:31] op_sel_hi:[1,0]
	v_pk_add_f32 v[2:3], v[98:99], v[30:31] op_sel_hi:[1,0]
	v_exp_f32_e32 v0, v0
	v_exp_f32_e32 v1, v1
	v_pk_add_f32 v[4:5], v[100:101], v[30:31] op_sel_hi:[1,0]
	v_exp_f32_e32 v2, v2
	v_exp_f32_e32 v3, v3
	v_exp_f32_e32 v4, v4
	v_exp_f32_e32 v5, v5
	v_pk_add_f32 v[6:7], v[102:103], v[30:31] op_sel_hi:[1,0]
	v_pk_add_f32 v[8:9], v[104:105], v[30:31] op_sel_hi:[1,0]
	v_exp_f32_e32 v6, v6
	v_exp_f32_e32 v7, v7
	v_exp_f32_e32 v8, v8
	v_exp_f32_e32 v9, v9
	v_pk_add_f32 v[10:11], v[2:3], v[0:1]
	v_pk_add_f32 v[12:13], v[108:109], v[30:31] op_sel_hi:[1,0]
	v_pk_add_f32 v[10:11], v[4:5], v[10:11]
	v_exp_f32_e32 v12, v12
	v_pk_add_f32 v[10:11], v[6:7], v[10:11]
	v_exp_f32_e32 v13, v13
	v_pk_add_f32 v[18:19], v[8:9], v[10:11]
	v_pk_add_f32 v[10:11], v[106:107], v[30:31] op_sel_hi:[1,0]
	v_pk_add_f32 v[14:15], v[110:111], v[30:31] op_sel_hi:[1,0]
	v_exp_f32_e32 v10, v10
	v_exp_f32_e32 v11, v11
	v_exp_f32_e32 v14, v14
	v_exp_f32_e32 v15, v15
	v_pk_add_f32 v[16:17], v[80:81], v[30:31] op_sel_hi:[1,0]
	v_pk_add_f32 v[18:19], v[10:11], v[18:19]
	v_exp_f32_e32 v16, v16
	v_exp_f32_e32 v17, v17
	v_pk_add_f32 v[18:19], v[12:13], v[18:19]
	v_pk_add_f32 v[20:21], v[84:85], v[30:31] op_sel_hi:[1,0]
	v_pk_add_f32 v[18:19], v[14:15], v[18:19]
	v_exp_f32_e32 v20, v20
	v_pk_add_f32 v[26:27], v[16:17], v[18:19]
	v_pk_add_f32 v[18:19], v[82:83], v[30:31] op_sel_hi:[1,0]
	v_exp_f32_e32 v21, v21
	v_exp_f32_e32 v18, v18
	v_exp_f32_e32 v19, v19
	v_pk_add_f32 v[22:23], v[86:87], v[30:31] op_sel_hi:[1,0]
	v_pk_add_f32 v[24:25], v[88:89], v[30:31] op_sel_hi:[1,0]
	v_exp_f32_e32 v22, v22
	v_exp_f32_e32 v23, v23
	v_exp_f32_e32 v24, v24
	v_exp_f32_e32 v25, v25
	v_pk_add_f32 v[26:27], v[18:19], v[26:27]
	v_sub_f32_e32 v32, v34, v201
	v_pk_add_f32 v[26:27], v[20:21], v[26:27]
	v_pk_add_f32 v[28:29], v[92:93], v[30:31] op_sel_hi:[1,0]
	v_pk_add_f32 v[26:27], v[22:23], v[26:27]
	v_exp_f32_e32 v28, v28
	v_pk_add_f32 v[34:35], v[24:25], v[26:27]
	v_pk_add_f32 v[26:27], v[90:91], v[30:31] op_sel_hi:[1,0]
	v_exp_f32_e32 v29, v29
	v_exp_f32_e32 v26, v26
	v_exp_f32_e32 v27, v27
	v_pk_add_f32 v[30:31], v[94:95], v[30:31] op_sel_hi:[1,0]
	v_exp_f32_e32 v30, v30
	v_exp_f32_e32 v31, v31
	v_pk_add_f32 v[34:35], v[26:27], v[34:35]
	v_exp_f32_e32 v32, v32
	v_pk_add_f32 v[34:35], v[28:29], v[34:35]
	v_cmp_gt_f32_e32 vcc, 1.0, v32
	v_pk_add_f32 v[34:35], v[30:31], v[34:35]
	s_nop 0
	v_add_f32_e32 v202, v34, v35
	v_fmac_f32_e32 v202, v36, v32
	s_cbranch_vccz .LBB0_852
